# token-shift norm loop: previous-row loads issued at the loop top together with the current row and gain loads
# speedup vs baseline: 1.0300x; 1.0024x over previous
.Lxm_plain_4096:
	global_load_dwordx4 v[100:103], v[82:83], off
	global_load_dwordx4 v[104:107], v[82:83], off offset:1024
	global_load_dwordx4 v[108:111], v[82:83], off offset:2048
	global_load_dwordx4 v[112:115], v[82:83], off offset:3072
	global_load_dwordx4 v[128:131], v[152:153], off offset:2048
	global_load_dwordx4 v[124:127], v[152:153], off offset:3072
	global_load_dwordx4 v[120:123], v[152:153], off offset:1024
	global_load_dwordx4 v[116:119], v[152:153], off
	s_add_i32 s42, s92, 0x407f
	s_ashr_i32 s43, s42, 31
	s_lshl_b64 s[42:43], s[42:43], 12
	v_lshl_add_u64 v[204:205], v[150:151], 0, s[42:43]
	s_cmpk_lt_i32 s92, 0xff80
	s_cbranch_scc1 .Lxm_pre_plain
	v_readlane_b32 vcc_lo, v250, 6
	v_and_b32_e32 v204, 63, v226
	v_lshlrev_b32_e32 v204, 4, v204
	v_lshl_add_u32 v204, vcc_lo, 13, v204
	v_mov_b32_e32 v205, 0
	v_readlane_b32 vcc_lo, v250, 13
	v_readlane_b32 vcc_hi, v250, 14
	s_nop 1
	v_lshl_add_u64 v[204:205], vcc, 0, v[204:205]
.Lxm_pre_plain:
	global_load_dwordx4 v[136:139], v[204:205], off
	global_load_dwordx4 v[144:147], v[204:205], off offset:1024
	global_load_dwordx4 v[132:135], v[204:205], off offset:2048
	global_load_dwordx4 v[140:143], v[204:205], off offset:3072
	s_cmpk_gt_i32 s7, 0x407f
	s_waitcnt vmcnt(11)
	v_pk_mul_f32 v[180:181], v[102:103], v[102:103]
	v_pk_mul_f32 v[182:183], v[100:101], v[100:101]
	s_nop 0
	v_pk_mov_b32 v[184:185], v[182:183], v[180:181] op_sel:[1,0]
	v_mov_b32_e32 v183, v181
	v_pk_add_f32 v[186:187], v[184:185], v[182:183]
	s_waitcnt vmcnt(10)
	v_pk_mul_f32 v[188:189], v[106:107], v[106:107]
	v_pk_mul_f32 v[190:191], v[104:105], v[104:105]
	s_nop 0
	v_pk_mov_b32 v[192:193], v[190:191], v[188:189] op_sel:[1,0]
	v_mov_b32_e32 v191, v189
	v_pk_add_f32 v[194:195], v[192:193], v[190:191]
	s_nop 0
	v_pk_add_f32 v[82:83], v[186:187], v[186:187] op_sel:[0,1] op_sel_hi:[1,0]
	v_pk_add_f32 v[186:187], v[194:195], v[194:195] op_sel:[0,1] op_sel_hi:[1,0]
	s_waitcnt vmcnt(8)
	v_mul_f32_e32 v80, v112, v112
	v_mul_f32_e32 v196, v113, v113
	v_mov_b32_e32 v83, v80
	v_mov_b32_e32 v187, v196
	v_mul_f32_e32 v80, v109, v109
	v_pk_add_f32 v[82:83], v[82:83], v[186:187]
	v_pk_fma_f32 v[186:187], v[108:109], v[108:109], v[80:81] op_sel_hi:[1,1,0]
	v_mul_f32_e32 v80, v111, v111
	v_mul_f32_e32 v197, v114, v114
	v_mul_f32_e32 v198, v115, v115
	v_pk_fma_f32 v[194:195], v[110:111], v[110:111], v[80:81] op_sel_hi:[1,1,0]
	v_mov_b32_e32 v187, v197
	v_mov_b32_e32 v195, v198
	v_pk_add_f32 v[186:187], v[186:187], v[194:195]
	s_nop 0
	v_pk_add_f32 v[82:83], v[82:83], v[186:187]
	s_nop 0
	v_add_f32_e32 v80, v82, v83
	ds_bpermute_b32 v82, v149, v80
	s_waitcnt lgkmcnt(0)
	v_add_f32_e32 v80, v80, v82
	ds_bpermute_b32 v82, v171, v80
	s_waitcnt lgkmcnt(0)
	v_add_f32_e32 v80, v80, v82
	ds_bpermute_b32 v82, v172, v80
	s_waitcnt lgkmcnt(0)
	v_add_f32_e32 v80, v80, v82
	ds_bpermute_b32 v82, v173, v80
	s_waitcnt lgkmcnt(0)
	v_add_f32_e32 v80, v80, v82
	ds_bpermute_b32 v82, v174, v80
	s_waitcnt lgkmcnt(0)
	v_add_f32_e32 v80, v80, v82
	ds_bpermute_b32 v82, v175, v80
	s_waitcnt lgkmcnt(0)
	v_add_f32_e32 v80, v80, v82
	v_fmamk_f32 v80, v80, 0x3a800000, v231
	v_cmp_gt_f32_e32 vcc, s48, v80
	v_mul_f32_e32 v82, 0x4f800000, v80
	s_nop 0
	v_cndmask_b32_e32 v80, v80, v82, vcc
	v_sqrt_f32_e32 v82, v80
	s_nop 0
	v_add_u32_e32 v83, -1, v82
	v_fma_f32 v200, -v83, v82, v80
	v_cmp_ge_f32_e64 s[42:43], 0, v200
	v_add_u32_e32 v200, 1, v82
	s_nop 0
	v_cndmask_b32_e64 v83, v82, v83, s[42:43]
	v_fma_f32 v82, -v200, v82, v80
	v_cmp_lt_f32_e64 s[42:43], 0, v82
	s_nop 1
	v_cndmask_b32_e64 v82, v83, v200, s[42:43]
	v_mul_f32_e32 v83, 0x37800000, v82
	v_cndmask_b32_e32 v82, v82, v83, vcc
	v_cmp_class_f32_e32 vcc, v80, v230
	s_nop 1
	v_cndmask_b32_e32 v80, v82, v80, vcc
	v_div_scale_f32 v82, s[18:19], v80, v80, 1.0
	v_rcp_f32_e32 v83, v82
	s_nop 0
	v_fma_f32 v200, -v82, v83, 1.0
	v_fmac_f32_e32 v83, v200, v83
	v_div_scale_f32 v200, vcc, 1.0, v80, 1.0
	v_mul_f32_e32 v201, v200, v83
	v_fma_f32 v202, -v82, v201, v200
	v_fmac_f32_e32 v201, v202, v83
	v_fma_f32 v82, -v82, v201, v200
	v_div_fmas_f32 v82, v82, v83, v201
	v_div_fixup_f32 v170, v82, v80, 1.0
	v_pk_mul_f32 v[82:83], v[100:101], v[170:171] op_sel_hi:[1,0]
	v_pk_mul_f32 v[100:101], v[102:103], v[170:171] op_sel_hi:[1,0]
	s_waitcnt vmcnt(4)
	v_pk_mul_f32 v[102:103], v[118:119], v[100:101]
	v_pk_mul_f32 v[100:101], v[116:117], v[82:83]
	v_pk_mul_f32 v[82:83], v[104:105], v[170:171] op_sel_hi:[1,0]
	v_pk_mul_f32 v[104:105], v[106:107], v[170:171] op_sel_hi:[1,0]
	s_nop 0
	v_pk_mul_f32 v[106:107], v[122:123], v[104:105]
	v_pk_mul_f32 v[104:105], v[120:121], v[82:83]
	v_pk_mul_f32 v[82:83], v[108:109], v[170:171] op_sel_hi:[1,0]
	v_pk_mul_f32 v[108:109], v[110:111], v[170:171] op_sel_hi:[1,0]
	s_nop 0
	v_pk_mul_f32 v[110:111], v[130:131], v[108:109]
	v_pk_mul_f32 v[108:109], v[128:129], v[82:83]
	s_cbranch_scc0 .LBB0_3466
	s_waitcnt vmcnt(0)
	s_lshl_b64 s[18:19], s[92:93], 12
	v_lshl_add_u64 v[140:141], v[154:155], 0, s[18:19]
	v_lshl_add_u64 v[82:83], v[156:157], 0, s[18:19]
	global_load_dwordx4 v[136:139], v[140:141], off
	s_nop 0
	global_store_dwordx4 v[82:83], v[100:103], off
	global_load_dwordx4 v[144:147], v[140:141], off offset:1024
	s_mov_b64 s[18:19], -1
	global_store_dwordx4 v[82:83], v[104:107], off offset:1024
	global_load_dwordx4 v[132:135], v[140:141], off offset:2048
	s_nop 0
	global_store_dwordx4 v[82:83], v[108:111], off offset:2048
	global_load_dwordx4 v[140:143], v[140:141], off offset:3072
	s_cbranch_execz .LBB0_3467
	s_branch .LBB0_3471

.Lxm_plain_0:
	s_waitcnt vmcnt(3)
	v_pk_mul_f32 v[204:205], v[138:139], v[138:139]
	v_pk_mul_f32 v[206:207], v[136:137], v[136:137]
	s_nop 0
	v_pk_mov_b32 v[208:209], v[206:207], v[204:205] op_sel:[1,0]
	v_mov_b32_e32 v207, v205
	v_pk_add_f32 v[158:159], v[208:209], v[206:207]
	s_waitcnt vmcnt(2)
	v_pk_mul_f32 v[204:205], v[146:147], v[146:147]
	v_pk_mul_f32 v[206:207], v[144:145], v[144:145]
	s_nop 0
	v_pk_mov_b32 v[208:209], v[206:207], v[204:205] op_sel:[1,0]
	v_mov_b32_e32 v207, v205
	v_pk_add_f32 v[160:161], v[208:209], v[206:207]
	s_nop 0
	v_pk_add_f32 v[82:83], v[158:159], v[158:159] op_sel:[0,1] op_sel_hi:[1,0]
	v_pk_add_f32 v[158:159], v[160:161], v[160:161] op_sel:[0,1] op_sel_hi:[1,0]
	s_waitcnt vmcnt(0)
	v_mul_f32_e32 v80, v140, v140
	v_mul_f32_e32 v176, v141, v141
	v_mov_b32_e32 v83, v80
	v_mov_b32_e32 v159, v176
	v_mul_f32_e32 v80, v133, v133
	v_pk_add_f32 v[82:83], v[82:83], v[158:159]
	v_pk_fma_f32 v[158:159], v[132:133], v[132:133], v[80:81] op_sel_hi:[1,1,0]
	v_mul_f32_e32 v80, v135, v135
	v_mul_f32_e32 v177, v142, v142
	v_mul_f32_e32 v178, v143, v143
	v_pk_fma_f32 v[160:161], v[134:135], v[134:135], v[80:81] op_sel_hi:[1,1,0]
	v_mov_b32_e32 v159, v177
	v_mov_b32_e32 v161, v178
	v_pk_add_f32 v[158:159], v[158:159], v[160:161]
	s_nop 0
	v_pk_add_f32 v[82:83], v[82:83], v[158:159]
	s_nop 0
	v_add_f32_e32 v80, v82, v83
	ds_bpermute_b32 v82, v149, v80
	s_waitcnt lgkmcnt(0)
	v_add_f32_e32 v80, v80, v82
	ds_bpermute_b32 v82, v171, v80
	s_waitcnt lgkmcnt(0)
	v_add_f32_e32 v80, v80, v82
	ds_bpermute_b32 v82, v172, v80
	s_waitcnt lgkmcnt(0)
	v_add_f32_e32 v80, v80, v82
	ds_bpermute_b32 v82, v173, v80
	s_waitcnt lgkmcnt(0)
	v_add_f32_e32 v80, v80, v82
	ds_bpermute_b32 v82, v174, v80
	s_waitcnt lgkmcnt(0)
	v_add_f32_e32 v80, v80, v82
	ds_bpermute_b32 v82, v175, v80
	s_waitcnt lgkmcnt(0)
	v_add_f32_e32 v80, v80, v82
	v_fmamk_f32 v80, v80, 0x3a800000, v231
	v_cmp_gt_f32_e32 vcc, s48, v80
	v_mul_f32_e32 v82, 0x4f800000, v80
	s_nop 0
	v_cndmask_b32_e32 v80, v80, v82, vcc
	v_sqrt_f32_e32 v82, v80
	s_nop 0
	v_add_u32_e32 v83, -1, v82
	v_fma_f32 v158, -v83, v82, v80
	v_cmp_ge_f32_e64 s[42:43], 0, v158
	v_add_u32_e32 v158, 1, v82
	s_nop 0
	v_cndmask_b32_e64 v83, v82, v83, s[42:43]
	v_fma_f32 v82, -v158, v82, v80
	v_cmp_lt_f32_e64 s[42:43], 0, v82
	s_nop 1
	v_cndmask_b32_e64 v82, v83, v158, s[42:43]
	v_mul_f32_e32 v83, 0x37800000, v82
	v_cndmask_b32_e32 v82, v82, v83, vcc
	v_cmp_class_f32_e32 vcc, v80, v230
	s_nop 1
	v_cndmask_b32_e32 v80, v82, v80, vcc
	v_div_scale_f32 v82, s[26:27], v80, v80, 1.0
	v_rcp_f32_e32 v83, v82
	s_nop 0
	v_fma_f32 v158, -v82, v83, 1.0
	v_fmac_f32_e32 v83, v158, v83
	v_div_scale_f32 v158, vcc, 1.0, v80, 1.0
	v_mul_f32_e32 v159, v158, v83
	v_fma_f32 v160, -v82, v159, v158
	v_fmac_f32_e32 v159, v160, v83
	v_fma_f32 v82, -v82, v159, v158
	v_div_fmas_f32 v82, v82, v83, v159
	v_div_fixup_f32 v80, v82, v80, 1.0
	v_pk_mul_f32 v[82:83], v[136:137], v[80:81] op_sel_hi:[1,0]
	v_pk_mul_f32 v[136:137], v[138:139], v[80:81] op_sel_hi:[1,0]
	s_nop 0
	v_pk_mul_f32 v[138:139], v[118:119], v[136:137]
	v_pk_mul_f32 v[136:137], v[116:117], v[82:83]
	v_pk_mul_f32 v[82:83], v[144:145], v[80:81] op_sel_hi:[1,0]
	v_pk_mul_f32 v[116:117], v[146:147], v[80:81] op_sel_hi:[1,0]
	v_pk_mul_f32 v[144:145], v[120:121], v[82:83]
	v_pk_mul_f32 v[146:147], v[122:123], v[116:117]
	v_pk_mul_f32 v[82:83], v[132:133], v[80:81] op_sel_hi:[1,0]
	v_pk_mul_f32 v[116:117], v[134:135], v[80:81] op_sel_hi:[1,0]
	v_pk_mul_f32 v[132:133], v[128:129], v[82:83]
	v_pk_mul_f32 v[134:135], v[130:131], v[116:117]
	v_pk_mul_f32 v[82:83], v[140:141], v[80:81] op_sel_hi:[1,0]
	v_pk_mul_f32 v[116:117], v[142:143], v[80:81] op_sel_hi:[1,0]
	v_pk_mul_f32 v[140:141], v[124:125], v[82:83]
	v_pk_mul_f32 v[142:143], v[126:127], v[116:117]
	s_cmpk_lg_i32 s7, 0xc78f
	s_cbranch_scc1 .LBB0_3470
